# v30 + blocks>=128 start G1/G3 2x s_sleep127 late
# speedup vs baseline: 1.0022x; 1.0017x over previous
;     __device__ void init(int N, int G, int c) { S.init(NBATCH * SEQ, N, G, c); }
; __global__ void __launch_bounds__(512, 2) hybrid_fwd(Params Parg) {
;     ...
;         { const Params P = fresh_params(); const int G = gridDim.x, blk = blockIdx.x;
;           pg8::Gemm g{(const pg8::bf16_t*)(P.ws + WS_H), (const pg8::bf16_t*)(P.ws + (size_t)(l & 1) * WS_WBUF + WS_W), ROWS, INW, DM}; pg8::StaticOrder S; S.init(ROWS, INW, G, blk);
;           pg8::EpiBf16<0> E{(pg8::bf16_t*)(P.ws + WS_PROJ), INW, nullptr, 0, 0, 1.0f};
;           pg8::gemm_phase<pg8::EpiBf16<0>, pg8::StaticOrder, true, true>(ldsl, g, S, E); }
.LBB0_157:
	s_or_b64 exec, exec, s[0:1]
	v_readlane_b32 s0, v255, 0
	v_readlane_b32 s1, v255, 1
	v_readlane_b32 s8, v253, 46
	s_bitcmp1_b32 s0, 0
	s_mov_b64 s[0:1], s[28:29]
	v_mov_b32_e32 v8, v200
	v_readlane_b32 s9, v253, 47
	s_waitcnt lgkmcnt(0)
	s_barrier
	s_cselect_b32 s70, 0x1800000, 0
	s_cmp_lt_u32 s2, 128
	s_cbranch_scc1 .Lg1st_go
	s_mov_b32 s100, 2

;     __device__ void init(int N, int G, int c) { S.init(NBATCH * SEQ, N, G, c); }
; __global__ void __launch_bounds__(512, 2) hybrid_fwd(Params Parg) {
;     ...
;         { const Params P = fresh_params(); const int G = gridDim.x, blk = blockIdx.x;
;           pg8::Gemm g{(const pg8::bf16_t*)(P.ws + WS_H), (const pg8::bf16_t*)(P.ws + (size_t)(l & 1) * WS_WBUF + WS_W_FI), ROWS, 2 * FFH, DM};
;           EpiSwiGLU E{(bf16_t*)(P.ws + WS_PROJ)};
;           if (lat_only) { LatOrder S; S.init(2 * FFH, G, blk); pg8::gemm_phase<EpiSwiGLU, LatOrder, true, true>(ldsl, g, S, E); }
;           else { pg8::StaticOrder S; S.init(ROWS, 2 * FFH, G, blk); pg8::gemm_phase<EpiSwiGLU, pg8::StaticOrder, true, true>(ldsl, g, S, E); } }
.LBB0_992:
	s_or_b64 exec, exec, s[10:11]
	s_mov_b64 s[0:1], s[18:19]
	s_waitcnt lgkmcnt(0)
	s_barrier
	s_cmp_lt_u32 s2, 128
	s_cbranch_scc1 .Lg3st_go
	s_mov_b32 s100, 2
